# x to bf16 conversion loop in phase 0 unrolled x4 (8 loads in flight per lane) on top of v8
# baseline (speedup 1.0000x reference)
.LBB0_78:
	s_mov_b32 s0, 0x200000
	s_lshl_b32 s4, s82, 9
	v_cmp_gt_i32_e32 vcc, s0, v0
	v_ashrrev_i32_e32 v1, 31, v0
	v_lshlrev_b32_e32 v58, 1, v0
	s_and_saveexec_b64 s[0:1], vcc
	v_readlane_b32 s48, v234, 7
	v_readlane_b32 s49, v234, 8
	v_readlane_b32 s50, v234, 9
	v_readlane_b32 s51, v234, 10
	v_readlane_b32 s52, v234, 11
	v_readlane_b32 s53, v234, 12
	v_readlane_b32 s54, v234, 13
	v_readlane_b32 s55, v234, 14
	v_readlane_b32 s56, v234, 15
	v_readlane_b32 s57, v234, 16
	v_readlane_b32 s58, v234, 17
	v_readlane_b32 s59, v234, 18
	v_readlane_b32 s60, v234, 19
	v_readlane_b32 s61, v234, 20
	v_readlane_b32 s62, v234, 21
	v_readlane_b32 s63, v234, 22
	s_cbranch_execz .LBB0_81
	v_lshl_add_u64 v[2:3], v[0:1], 4, s[84:85]
	s_mov_b64 s[6:7], 0xe400000
	s_ashr_i32 s5, s4, 31
	s_mov_b64 s[12:13], s[48:49]
	v_lshl_add_u64 v[2:3], v[2:3], 0, s[6:7]
	s_lshl_b64 s[6:7], s[4:5], 4
	v_lshlrev_b32_e32 v4, 1, v0
	s_lshl_b32 s5, s82, 10
	s_mov_b64 s[8:9], 0
	s_mov_b32 s10, 0x1fffff
	v_mov_b32_e32 v6, v0
	s_mul_i32 s11, s4, 3
	s_mov_b64 s[14:15], exec
	s_mov_b32 s16, 0x200000
	s_lshl_b32 s17, s4, 2
	s_lshl_b32 s20, s4, 3
	s_lshl_b64 s[18:19], s[6:7], 1
.Lxcv4_top:
	v_add_u32_e32 v7, s11, v6
	v_cmp_gt_i32_e32 vcc, s16, v7
	s_and_b64 exec, s[14:15], vcc
	s_cbranch_execz .Lxcv4_done
	v_ashrrev_i32_e32 v5, 31, v4
	v_lshl_add_u64 v[46:47], v[4:5], 4, s[12:13]
	v_lshl_add_u64 v[48:49], v[46:47], 0, s[18:19]
	v_lshl_add_u64 v[50:51], v[48:49], 0, s[18:19]
	v_lshl_add_u64 v[52:53], v[50:51], 0, s[18:19]
	global_load_dwordx4 v[8:11], v[46:47], off
	global_load_dwordx4 v[12:15], v[46:47], off offset:16
	global_load_dwordx4 v[16:19], v[48:49], off
	global_load_dwordx4 v[20:23], v[48:49], off offset:16
	global_load_dwordx4 v[24:27], v[50:51], off
	global_load_dwordx4 v[28:31], v[50:51], off offset:16
	global_load_dwordx4 v[32:35], v[52:53], off
	global_load_dwordx4 v[36:39], v[52:53], off offset:16
	v_add_u32_e32 v6, s17, v6
	v_add_u32_e32 v4, s20, v4
	s_waitcnt vmcnt(6)
	v_cvt_pk_bf16_f32 v8, v8, v9
	v_cvt_pk_bf16_f32 v9, v10, v11
	v_cvt_pk_bf16_f32 v10, v12, v13
	v_cvt_pk_bf16_f32 v11, v14, v15
	global_store_dwordx4 v[2:3], v[8:11], off
	v_lshl_add_u64 v[2:3], v[2:3], 0, s[6:7]
	s_waitcnt vmcnt(5)
	v_cvt_pk_bf16_f32 v16, v16, v17
	v_cvt_pk_bf16_f32 v17, v18, v19
	v_cvt_pk_bf16_f32 v18, v20, v21
	v_cvt_pk_bf16_f32 v19, v22, v23
	global_store_dwordx4 v[2:3], v[16:19], off
	v_lshl_add_u64 v[2:3], v[2:3], 0, s[6:7]
	s_waitcnt vmcnt(4)
	v_cvt_pk_bf16_f32 v24, v24, v25
	v_cvt_pk_bf16_f32 v25, v26, v27
	v_cvt_pk_bf16_f32 v26, v28, v29
	v_cvt_pk_bf16_f32 v27, v30, v31
	global_store_dwordx4 v[2:3], v[24:27], off
	v_lshl_add_u64 v[2:3], v[2:3], 0, s[6:7]
	s_waitcnt vmcnt(3)
	v_cvt_pk_bf16_f32 v32, v32, v33
	v_cvt_pk_bf16_f32 v33, v34, v35
	v_cvt_pk_bf16_f32 v34, v36, v37
	v_cvt_pk_bf16_f32 v35, v38, v39
	global_store_dwordx4 v[2:3], v[32:35], off
	v_lshl_add_u64 v[2:3], v[2:3], 0, s[6:7]
	s_branch .Lxcv4_top
.Lxcv4_done:
	v_cmp_gt_i32_e32 vcc, s16, v6
	s_and_b64 exec, s[14:15], vcc
	s_mov_b64 s[8:9], 0
	s_cbranch_execz .LBB0_81
